# instruction selection in top-k rounds: selected-bit computed arithmetically (drops 16 cndmask + 9 or per round) + mask rotation; on top of permlane merge + max3 interleave
# speedup vs baseline: 1.0054x; 1.0054x over previous
; template <int CTRL> DI float dpp_f(float x) { return __builtin_bit_cast(float, __builtin_amdgcn_update_dpp(0, __builtin_bit_cast(int, x), CTRL, 0xF, 0xF, true)); }
; template <int CTRL> DI int dpp_i(int x) { return __builtin_amdgcn_update_dpp(0, x, CTRL, 0xF, 0xF, true); }
; template <int DV>
; DI void attn_unit(const int wv, const Args& A, LAS unsigned char* lds, int b, int g, int qb, int dry) {
;     ...
;             for (int round = 0; round < 13; ++round) {
;                 float lm = sc[0];
; #pragma unroll
;                 for (int i = 1; i < 16; ++i) lm = fmaxf(lm, sc[i]);
;                 lm = fmaxf(lm, dpp_f<0xB1>(lm)); lm = fmaxf(lm, dpp_f<0x4E>(lm)); lm = fmaxf(lm, dpp_f<0x141>(lm));
;                 int li = 99;
; #pragma unroll
;                 for (int i = 15; i >= 0; --i) li = (sc[i] == lm) ? i : li;
;                 int cj = (li < 16) ? (l8 + 8 * li) : 999;
;                 cj = min(cj, dpp_i<0xB1>(cj)); cj = min(cj, dpp_i<0x4E>(cj)); cj = min(cj, dpp_i<0x141>(cj));
;                 const int tt = cj - l8;
; #pragma unroll
;                 for (int i = 0; i < 16; ++i) { const bool hit = (tt == 8 * i); sc[i] = hit ? -1.f : sc[i]; selm |= hit ? (1u << i) : 0u; }
;             }
; #pragma unroll
;             for (int i = 0; i < 16; ++i) { if ((selm >> i) & 1u) { if (i < 8) slo |= 1ull << (l8 + 8 * i); else shi |= 1ull << (l8 + 8 * (i - 8)); } }
.LBB0_868:
	s_waitcnt lgkmcnt(0)
	v_max_f32_e32 v58, v0, v0
	v_max_f32_e32 v60, v1, v1
	v_max_f32_e32 v58, v60, v58
	v_max3_f32 v58, v58, v41, v39
	v_max3_f32 v58, v58, v46, v45
	v_max3_f32 v58, v58, v49, v48
	v_max3_f32 v58, v58, v51, v50
	v_max3_f32 v58, v58, v53, v52
	v_max3_f32 v58, v58, v55, v54
	v_max3_f32 v58, v58, v57, v56
	s_add_i32 s8, s8, -1
	s_cmp_eq_u32 s8, 0
	v_max_f32_dpp v58, v58, v58 quad_perm:[1,0,3,2] row_mask:0xf bank_mask:0xf bound_ctrl:1
	s_nop 1
	v_max_f32_dpp v58, v58, v58 quad_perm:[2,3,0,1] row_mask:0xf bank_mask:0xf bound_ctrl:1
	s_nop 1
	v_max_f32_dpp v58, v58, v58 row_half_mirror row_mask:0xf bank_mask:0xf bound_ctrl:1
	v_cmp_eq_f32_e32 vcc, v56, v58
	v_cmp_neq_f32_e64 s[100:101], v57, v58
	v_cmp_neq_f32_e64 s[98:99], v54, v58
	v_cndmask_b32_e64 v60, v205, 15, vcc
	v_cmp_neq_f32_e32 vcc, v55, v58
	v_cndmask_b32_e64 v60, 14, v60, s[100:101]
	v_cmp_neq_f32_e64 s[100:101], v52, v58
	v_cndmask_b32_e64 v60, 13, v60, s[98:99]
	v_cmp_neq_f32_e64 s[98:99], v53, v58
	v_cndmask_b32_e64 v60, 12, v60, vcc
	v_cmp_neq_f32_e32 vcc, v50, v58
	v_cndmask_b32_e64 v60, 11, v60, s[100:101]
	v_cmp_neq_f32_e64 s[100:101], v51, v58
	v_cndmask_b32_e64 v60, 10, v60, s[98:99]
	v_cmp_neq_f32_e64 s[98:99], v48, v58
	v_cndmask_b32_e64 v60, 9, v60, vcc
	v_cmp_neq_f32_e32 vcc, v49, v58
	v_cndmask_b32_e64 v60, 8, v60, s[100:101]
	v_cmp_neq_f32_e64 s[100:101], v45, v58
	v_cndmask_b32_e64 v60, 7, v60, s[98:99]
	v_cmp_neq_f32_e64 s[98:99], v46, v58
	v_cndmask_b32_e64 v60, 6, v60, vcc
	v_cmp_neq_f32_e32 vcc, v39, v58
	v_cndmask_b32_e64 v60, 5, v60, s[100:101]
	v_cmp_neq_f32_e64 s[100:101], v41, v58
	v_cndmask_b32_e64 v60, 4, v60, s[98:99]
	v_cmp_neq_f32_e64 s[98:99], v0, v58
	v_cndmask_b32_e64 v60, 3, v60, vcc
	v_cmp_neq_f32_e32 vcc, v1, v58
	v_cndmask_b32_e64 v60, 2, v60, s[100:101]
	v_cndmask_b32_e64 v60, 1, v60, s[98:99]
	v_cndmask_b32_e64 v58, 0, v60, vcc
	v_cmp_gt_u32_e32 vcc, 16, v58
	v_lshl_or_b32 v58, v58, 3, v40
	s_nop 0
	v_cndmask_b32_e32 v58, v206, v58, vcc
	s_nop 1
	v_min_i32_dpp v58, v58, v58 quad_perm:[1,0,3,2] row_mask:0xf bank_mask:0xf bound_ctrl:1
	s_nop 1
	v_min_i32_dpp v58, v58, v58 quad_perm:[2,3,0,1] row_mask:0xf bank_mask:0xf bound_ctrl:1
	s_nop 1
	v_min_i32_dpp v58, v58, v58 row_half_mirror row_mask:0xf bank_mask:0xf bound_ctrl:1
	v_sub_u32_e32 v67, v58, v40
	v_cmp_eq_u32_e32 vcc, v58, v40
	v_cmp_eq_u32_e64 s[98:99], 8, v67
	v_cmp_eq_u32_e64 s[100:101], 16, v67
	v_cndmask_b32_e64 v1, v1, -1.0, vcc
	v_cmp_eq_u32_e32 vcc, 24, v67
	v_cndmask_b32_e64 v0, v0, -1.0, s[98:99]
	v_cmp_eq_u32_e64 s[98:99], 32, v67
	v_cndmask_b32_e64 v41, v41, -1.0, s[100:101]
	v_cmp_eq_u32_e64 s[100:101], 40, v67
	v_cndmask_b32_e64 v39, v39, -1.0, vcc
	v_cmp_eq_u32_e32 vcc, 48, v67
	v_cndmask_b32_e64 v46, v46, -1.0, s[98:99]
	v_cmp_eq_u32_e64 s[98:99], 56, v67
	v_cndmask_b32_e64 v45, v45, -1.0, s[100:101]
	v_cmp_eq_u32_e64 s[100:101], 64, v67
	v_cndmask_b32_e64 v49, v49, -1.0, vcc
	v_cmp_eq_u32_e32 vcc, 0x48, v67
	v_cndmask_b32_e64 v48, v48, -1.0, s[98:99]
	s_movk_i32 s9, 0x50
	v_cmp_eq_u32_e64 s[98:99], s9, v67
	v_cndmask_b32_e64 v51, v51, -1.0, s[100:101]
	s_movk_i32 s9, 0x58
	v_cmp_eq_u32_e64 s[100:101], s9, v67
	v_cndmask_b32_e64 v50, v50, -1.0, vcc
	v_cmp_eq_u32_e32 vcc, 0x60, v67
	v_cndmask_b32_e64 v53, v53, -1.0, s[98:99]
	s_movk_i32 s9, 0x68
	v_cmp_eq_u32_e64 s[98:99], s9, v67
	v_cndmask_b32_e64 v52, v52, -1.0, s[100:101]
	s_movk_i32 s9, 0x70
	v_cmp_eq_u32_e64 s[100:101], s9, v67
	v_cndmask_b32_e64 v55, v55, -1.0, vcc
	v_cmp_eq_u32_e32 vcc, 0x78, v67
	v_cndmask_b32_e64 v54, v54, -1.0, s[98:99]
	v_cndmask_b32_e64 v57, v57, -1.0, s[100:101]
	v_cndmask_b32_e64 v56, v56, -1.0, vcc
	v_and_b32_e32 v60, 0xffffff87, v67
	v_lshrrev_b32_e32 v61, 3, v67
	v_cmp_eq_u32_e32 vcc, 0, v60
	v_lshlrev_b32_e64 v61, v61, 1
	s_nop 0
	v_cndmask_b32_e32 v61, 0, v61, vcc
	v_or_b32_e32 v59, v59, v61
	s_cbranch_scc0 .LBB0_868
	v_mov_b32_e32 v63, v59
	v_mov_b32_e32 v62, v59
	v_mov_b32_e32 v61, v59
	v_mov_b32_e32 v60, v59
	v_mov_b32_e32 v58, v59
	v_mov_b32_e32 v64, v59
	v_mov_b32_e32 v65, v59
	v_mov_b32_e32 v66, v59
	v_and_b32_e32 v0, 1, v63
	v_lshlrev_b64 v[48:49], v40, 1
	v_cmp_eq_u32_e32 vcc, 1, v0
	v_lshlrev_b64 v[50:51], v36, 1
	v_and_b32_e32 v36, 2, v62
	v_cndmask_b32_e32 v0, 0, v49, vcc
	v_cndmask_b32_e32 v1, 0, v48, vcc
	v_cmp_ne_u32_e32 vcc, 0, v36
	v_and_b32_e32 v46, 8, v61
	v_and_b32_e32 v55, 0x80, v58
	v_cndmask_b32_e32 v39, 0, v50, vcc
	v_cndmask_b32_e32 v36, 0, v51, vcc
	v_or_b32_e32 v1, v39, v1
	v_and_b32_e32 v39, 4, v61
	v_or_b32_e32 v0, v36, v0
	v_lshlrev_b64 v[36:37], v37, 1
	v_cmp_ne_u32_e32 vcc, 0, v39
	v_lshlrev_b64 v[38:39], v38, 1
	s_mov_b64 s[8:9], 0
	v_cndmask_b32_e32 v41, 0, v37, vcc
	v_cndmask_b32_e32 v45, 0, v36, vcc
	v_cmp_ne_u32_e32 vcc, 0, v46
	s_nop 1
	v_cndmask_b32_e32 v46, 0, v39, vcc
	v_cndmask_b32_e32 v52, 0, v38, vcc
	v_or3_b32 v0, v0, v41, v46
	v_and_b32_e32 v41, 16, v60
	v_or3_b32 v1, v1, v45, v52
	v_lshlrev_b64 v[52:53], v42, 1
	v_cmp_ne_u32_e32 vcc, 0, v41
	v_and_b32_e32 v46, 32, v60
	v_lshlrev_b64 v[42:43], v43, 1
	v_cndmask_b32_e32 v41, 0, v53, vcc
	v_cndmask_b32_e32 v45, 0, v52, vcc
	v_cmp_ne_u32_e32 vcc, 0, v46
	s_nop 1
	v_cndmask_b32_e32 v46, 0, v43, vcc
	v_cndmask_b32_e32 v54, 0, v42, vcc
	v_or3_b32 v0, v0, v41, v46
	v_or3_b32 v41, v1, v45, v54
	v_and_b32_e32 v1, 64, v58
	v_lshlrev_b64 v[44:45], v44, 1
	v_cmp_ne_u32_e32 vcc, 0, v1
	v_lshlrev_b64 v[46:47], v47, 1
	s_nop 0
	v_cndmask_b32_e32 v1, 0, v45, vcc
	v_cndmask_b32_e32 v54, 0, v44, vcc
	v_cmp_ne_u32_e32 vcc, 0, v55
	s_nop 1
	v_cndmask_b32_e32 v55, 0, v47, vcc
	v_cndmask_b32_e32 v56, 0, v46, vcc
	v_or3_b32 v1, v0, v1, v55
	v_or3_b32 v0, v41, v54, v56
	v_and_b32_e32 v41, 0x100, v64
	v_cmp_ne_u32_e32 vcc, 0, v41
	s_nop 1
	v_cndmask_b32_e32 v41, 0, v49, vcc
	v_and_b32_e32 v49, 0x200, v64
	v_cndmask_b32_e32 v48, 0, v48, vcc
	v_cmp_ne_u32_e32 vcc, 0, v49
	s_nop 1
	v_cndmask_b32_e32 v49, 0, v51, vcc
	v_or_b32_e32 v41, v41, v49
	v_and_b32_e32 v49, 0x400, v65
	v_cndmask_b32_e32 v50, 0, v50, vcc
	v_cmp_ne_u32_e32 vcc, 0, v49
	v_and_b32_e32 v49, 0x800, v65
	v_or_b32_e32 v48, v48, v50
	v_cndmask_b32_e32 v37, 0, v37, vcc
	v_cndmask_b32_e32 v36, 0, v36, vcc
	v_cmp_ne_u32_e32 vcc, 0, v49
	s_nop 1
	v_cndmask_b32_e32 v38, 0, v38, vcc
	v_cndmask_b32_e32 v39, 0, v39, vcc
	v_or3_b32 v36, v48, v36, v38
	v_and_b32_e32 v38, 0x1000, v66
	v_or3_b32 v37, v41, v37, v39
	v_cmp_ne_u32_e32 vcc, 0, v38
	v_and_b32_e32 v41, 0x2000, v66
	s_nop 0
	v_cndmask_b32_e32 v38, 0, v53, vcc
	v_cndmask_b32_e32 v39, 0, v52, vcc
	v_cmp_ne_u32_e32 vcc, 0, v41
	s_nop 1
	v_cndmask_b32_e32 v41, 0, v43, vcc
	v_or3_b32 v37, v37, v38, v41
	v_and_b32_e32 v38, 0x4000, v59
	v_cndmask_b32_e32 v42, 0, v42, vcc
	v_cmp_ne_u32_e32 vcc, 0, v38
	v_and_b32_e32 v41, 0x8000, v59
	v_or3_b32 v36, v36, v39, v42
	v_cndmask_b32_e32 v38, 0, v45, vcc
	v_cndmask_b32_e32 v39, 0, v44, vcc
	v_cmp_ne_u32_e32 vcc, 0, v41
	s_nop 1
	v_cndmask_b32_e32 v41, 0, v47, vcc
	v_cndmask_b32_e32 v42, 0, v46, vcc
	v_or3_b32 v37, v37, v38, v41
	v_or3_b32 v36, v36, v39, v42
